# norm2 (layer 0) token loop: norm-weight/scale/shift chunk loads 1..3 issued with chunk 0, per-chunk vmcnt waits dropped (stores no longer drained per chunk)
# baseline (speedup 1.0000x reference)
.LBB0_909:
	v_mul_hi_i32 v3, v2, s41
	v_lshrrev_b32_e32 v13, 31, v3
	v_ashrrev_i32_e32 v3, 9, v3
	v_add_u32_e32 v13, v3, v13
	v_mad_i32_i24 v3, v13, s42, v2
	v_cmp_gt_i32_e64 s[6:7], s40, v3
	v_cmp_lt_i32_e32 vcc, s43, v3
	s_and_saveexec_b64 s[0:1], vcc
	s_xor_b64 s[0:1], exec, s[0:1]
	v_mul_i32_i24_e32 v3, 0xfffff700, v13
	v_lshl_add_u32 v3, v13, 11, v3
	v_add3_u32 v18, v2, v3, s44
	s_or_saveexec_b64 s[0:1], s[0:1]
	v_mov_b64_e32 v[20:21], s[28:29]
	s_xor_b64 exec, exec, s[0:1]
	v_lshl_add_u32 v18, v13, 8, v3
	v_mov_b64_e32 v[20:21], s[18:19]
	s_or_b64 exec, exec, s[0:1]
	v_ashrrev_i32_e32 v19, 31, v18
	v_lshlrev_b64 v[18:19], 12, v[18:19]
	v_lshl_add_u64 v[18:19], v[20:21], 0, v[18:19]
	v_lshl_add_u64 v[18:19], v[18:19], 0, v[10:11]
	global_load_dwordx2 v[26:27], v[18:19], off
	global_load_dwordx2 v[24:25], v[18:19], off offset:512
	global_load_dwordx2 v[20:21], v[18:19], off offset:1024
	global_load_dwordx2 v[22:23], v[18:19], off offset:1536
	v_add_u32_e32 v67, s37, v2
	v_min_i32_e32 v38, 0x8fff, v67
	v_mul_hi_i32 v3, v38, s41
	v_lshrrev_b32_e32 v15, 31, v3
	v_ashrrev_i32_e32 v3, 9, v3
	v_add_u32_e32 v39, v3, v15
	v_mad_i32_i24 v3, v39, s42, v38
	v_cmp_gt_i32_e64 s[4:5], s40, v3
	v_cmp_lt_i32_e32 vcc, s43, v3
	s_and_saveexec_b64 s[0:1], vcc
	s_xor_b64 s[0:1], exec, s[0:1]
	v_lshlrev_b32_e32 v15, 11, v39
	v_add3_u32 v18, v15, v3, s44
	s_or_saveexec_b64 s[0:1], s[0:1]
	v_mov_b64_e32 v[28:29], s[28:29]
	s_xor_b64 exec, exec, s[0:1]
	v_lshl_add_u32 v18, v39, 8, v3
	v_mov_b64_e32 v[28:29], s[18:19]
	s_or_b64 exec, exec, s[0:1]
	v_ashrrev_i32_e32 v19, 31, v18
	v_lshlrev_b64 v[18:19], 12, v[18:19]
	v_lshl_add_u64 v[18:19], v[28:29], 0, v[18:19]
	v_lshl_add_u64 v[18:19], v[18:19], 0, v[10:11]
	global_load_dwordx2 v[46:47], v[18:19], off
	global_load_dwordx2 v[44:45], v[18:19], off offset:512
	global_load_dwordx2 v[40:41], v[18:19], off offset:1024
	global_load_dwordx2 v[42:43], v[18:19], off offset:1536
	v_add_u32_e32 v66, s17, v2
	v_min_i32_e32 v28, 0x8fff, v66
	v_mul_hi_i32 v3, v28, s41
	v_lshrrev_b32_e32 v15, 31, v3
	v_ashrrev_i32_e32 v3, 9, v3
	v_add_u32_e32 v29, v3, v15
	v_mad_i32_i24 v3, v29, s42, v28
	v_cmp_gt_i32_e64 s[2:3], s40, v3
	v_cmp_lt_i32_e32 vcc, s43, v3
	s_and_saveexec_b64 s[0:1], vcc
	s_xor_b64 s[0:1], exec, s[0:1]
	v_lshlrev_b32_e32 v15, 11, v29
	v_add3_u32 v18, v15, v3, s44
	s_or_saveexec_b64 s[0:1], s[0:1]
	v_mov_b64_e32 v[30:31], s[28:29]
	s_xor_b64 exec, exec, s[0:1]
	v_lshl_add_u32 v18, v29, 8, v3
	v_mov_b64_e32 v[30:31], s[18:19]
	s_or_b64 exec, exec, s[0:1]
	v_ashrrev_i32_e32 v19, 31, v18
	v_lshlrev_b64 v[18:19], 12, v[18:19]
	v_lshl_add_u64 v[18:19], v[30:31], 0, v[18:19]
	v_lshl_add_u64 v[18:19], v[18:19], 0, v[10:11]
	global_load_dwordx2 v[36:37], v[18:19], off
	global_load_dwordx2 v[34:35], v[18:19], off offset:512
	global_load_dwordx2 v[30:31], v[18:19], off offset:1024
	global_load_dwordx2 v[32:33], v[18:19], off offset:1536
	v_add_u32_e32 v19, s74, v2
	v_min_i32_e32 v18, 0x8fff, v19
	v_mul_hi_i32 v3, v18, s41
	v_lshrrev_b32_e32 v15, 31, v3
	v_ashrrev_i32_e32 v3, 9, v3
	v_add_u32_e32 v3, v3, v15
	v_mad_i32_i24 v15, v3, s42, v18
	v_cmp_gt_i32_e32 vcc, s40, v15
	v_cmp_lt_i32_e64 s[0:1], s43, v15
	s_and_saveexec_b64 s[48:49], s[0:1]
	s_xor_b64 s[0:1], exec, s[48:49]
	v_lshlrev_b32_e32 v17, 11, v3
	v_add3_u32 v60, v17, v15, s44
	s_or_saveexec_b64 s[0:1], s[0:1]
	v_mov_b64_e32 v[62:63], s[28:29]
	s_xor_b64 exec, exec, s[0:1]
	v_lshl_add_u32 v60, v3, 8, v15
	v_mov_b64_e32 v[62:63], s[18:19]
	s_or_b64 exec, exec, s[0:1]
	v_cndmask_b32_e64 v13, v13, 16, s[6:7]
	v_mul_hi_i32_i24_e32 v49, 0x6000, v13
	v_mul_i32_i24_e32 v48, 0x6000, v13
	v_lshl_add_u64 v[48:49], s[12:13], 0, v[48:49]
	v_lshl_add_u64 v[56:57], v[48:49], 0, s[22:23]
	v_lshl_add_u64 v[54:55], v[48:49], 0, s[24:25]
	v_lshl_add_u64 v[48:49], v[56:57], 0, v[0:1]
	global_load_dwordx4 v[68:71], v[4:5], off
	global_load_dwordx4 v[72:75], v[48:49], off
	v_lshl_add_u64 v[48:49], v[54:55], 0, v[0:1]
	global_load_dwordx4 v[76:79], v[48:49], off
	global_load_dwordx4 v[92:95], v[4:5], off offset:1024
	v_mov_b32_e32 v128, v12
	v_mov_b32_e32 v129, v1
	v_lshl_add_u64 v[130:131], v[56:57], 0, v[128:129]
	global_load_dwordx4 v[96:99], v[130:131], off
	v_mov_b32_e32 v128, v12
	v_mov_b32_e32 v129, v1
	v_lshl_add_u64 v[130:131], v[54:55], 0, v[128:129]
	global_load_dwordx4 v[100:103], v[130:131], off
	global_load_dwordx4 v[104:107], v[4:5], off offset:2048
	v_mov_b32_e32 v128, v14
	v_mov_b32_e32 v129, v1
	v_lshl_add_u64 v[130:131], v[56:57], 0, v[128:129]
	global_load_dwordx4 v[108:111], v[130:131], off
	v_mov_b32_e32 v128, v14
	v_mov_b32_e32 v129, v1
	v_lshl_add_u64 v[130:131], v[54:55], 0, v[128:129]
	global_load_dwordx4 v[112:115], v[130:131], off
	global_load_dwordx4 v[116:119], v[4:5], off offset:3072
	v_mov_b32_e32 v128, v16
	v_mov_b32_e32 v129, v1
	v_lshl_add_u64 v[130:131], v[56:57], 0, v[128:129]
	global_load_dwordx4 v[120:123], v[130:131], off
	v_mov_b32_e32 v128, v16
	v_mov_b32_e32 v129, v1
	v_lshl_add_u64 v[130:131], v[54:55], 0, v[128:129]
	global_load_dwordx4 v[124:127], v[130:131], off
	s_waitcnt vmcnt(0)
	v_and_b32_e32 v82, 0xffff0000, v26
	v_and_b32_e32 v86, 0xffff0000, v24
	v_ashrrev_i32_e32 v61, 31, v60
	v_lshlrev_b32_e32 v80, 16, v26
	v_lshlrev_b32_e32 v85, 16, v25
	v_lshlrev_b32_e32 v84, 16, v24
	v_and_b32_e32 v87, 0xffff0000, v25
	v_lshlrev_b32_e32 v58, 16, v20
	v_and_b32_e32 v49, 0xffff0000, v22
	v_and_b32_e32 v48, 0xffff0000, v20
	v_lshlrev_b32_e32 v52, 16, v21
	v_and_b32_e32 v50, 0xffff0000, v21
	v_lshlrev_b64 v[20:21], 12, v[60:61]
	v_mov_b32_e32 v24, v82
	v_mov_b32_e32 v25, v86
	v_lshlrev_b32_e32 v81, 16, v27
	v_lshlrev_b32_e32 v59, 16, v22
	v_lshlrev_b32_e32 v53, 16, v23
	v_and_b32_e32 v51, 0xffff0000, v23
	v_mov_b32_e32 v22, v80
	v_mov_b32_e32 v23, v84
	v_pk_mul_f32 v[88:89], v[48:49], v[48:49]
	v_lshl_add_u64 v[20:21], v[62:63], 0, v[20:21]
	v_pk_mul_f32 v[24:25], v[24:25], v[24:25]
	v_and_b32_e32 v83, 0xffff0000, v27
	v_mov_b32_e32 v26, v81
	v_mov_b32_e32 v27, v85
	v_pk_fma_f32 v[62:63], v[58:59], v[58:59], v[88:89]
	v_lshl_add_u64 v[88:89], v[20:21], 0, v[10:11]
	v_pk_fma_f32 v[20:21], v[22:23], v[22:23], v[24:25]
	v_mov_b32_e32 v60, v83
	v_mov_b32_e32 v61, v87
	v_pk_fma_f32 v[20:21], v[26:27], v[26:27], v[20:21]
	v_pk_fma_f32 v[22:23], v[52:53], v[52:53], v[62:63]
	v_pk_fma_f32 v[20:21], v[60:61], v[60:61], v[20:21]
	v_pk_fma_f32 v[22:23], v[50:51], v[50:51], v[22:23]
	v_add_f32_e32 v13, v20, v21
	v_add_f32_e32 v13, v13, v22
	v_add_f32_e32 v13, v13, v23
	s_nop 1
	v_add_f32_dpp v13, v13, v13 quad_perm:[1,0,3,2] row_mask:0xf bank_mask:0xf bound_ctrl:1
	s_nop 1
	v_add_f32_dpp v13, v13, v13 quad_perm:[2,3,0,1] row_mask:0xf bank_mask:0xf bound_ctrl:1
	s_nop 1
	v_add_f32_dpp v13, v13, v13 row_half_mirror row_mask:0xf bank_mask:0xf bound_ctrl:1
	s_nop 1
	v_add_f32_dpp v13, v13, v13 row_mirror row_mask:0xf bank_mask:0xf bound_ctrl:1
	s_nop 0
	v_readlane_b32 s6, v13, 16
	v_readlane_b32 s7, v13, 48
	v_readlane_b32 s0, v13, 0
	v_readlane_b32 s1, v13, 32
	v_mov_b32_e32 v20, s6
	v_mov_b32_e32 v21, s7
	v_pk_add_f32 v[20:21], s[0:1], v[20:21]
	s_nop 0
	v_add_f32_e32 v13, v20, v21
	v_fmamk_f32 v13, v13, 0x3a800000, v64
	v_mul_f32_e32 v15, 0x4b800000, v13
	v_cmp_gt_f32_e64 s[0:1], s46, v13
	global_load_dwordx2 v[26:27], v[88:89], off
	global_load_dwordx2 v[24:25], v[88:89], off offset:512
	global_load_dwordx2 v[20:21], v[88:89], off offset:1024
	global_load_dwordx2 v[22:23], v[88:89], off offset:1536
	v_cndmask_b32_e64 v13, v13, v15, s[0:1]
	v_rsq_f32_e32 v13, v13
	s_nop 0
	v_mul_f32_e32 v15, 0x45800000, v13
	v_cndmask_b32_e64 v88, v13, v15, s[0:1]
	v_pk_mul_f32 v[60:61], v[88:89], v[80:81] op_sel_hi:[0,1]
	v_pk_mul_f32 v[62:63], v[88:89], v[82:83] op_sel_hi:[0,1]
	v_cmp_gt_i32_e64 s[0:1], s39, v67
	s_waitcnt lgkmcnt(0)
	v_mov_b32_e32 v80, v68
	v_mov_b32_e32 v81, v70
	v_mov_b32_e32 v70, v69
	v_mov_b32_e32 v68, v72
	v_mov_b32_e32 v69, v74
	v_pk_mul_f32 v[60:61], v[80:81], v[60:61]
	v_pk_mul_f32 v[62:63], v[70:71], v[62:63]
	v_mov_b32_e32 v70, v76
	v_mov_b32_e32 v71, v78
	v_mov_b32_e32 v74, v73
	v_pk_add_f32 v[68:69], v[68:69], 1.0 op_sel_hi:[1,0]
	v_pk_add_f32 v[72:73], v[74:75], 1.0 op_sel_hi:[1,0]
	v_pk_fma_f32 v[60:61], v[68:69], v[60:61], v[70:71]
	v_mov_b32_e32 v78, v77
	v_pk_fma_f32 v[62:63], v[72:73], v[62:63], v[78:79]
	v_and_b32_sdwa v15, v60, v65 dst_sel:DWORD dst_unused:UNUSED_PAD src0_sel:WORD_1 src1_sel:DWORD
	v_add3_u32 v15, v60, v15, s47
	v_and_b32_sdwa v17, v63, v65 dst_sel:DWORD dst_unused:UNUSED_PAD src0_sel:WORD_1 src1_sel:DWORD
	v_and_b32_sdwa v60, v62, v65 dst_sel:DWORD dst_unused:UNUSED_PAD src0_sel:WORD_1 src1_sel:DWORD
	v_and_b32_sdwa v13, v61, v65 dst_sel:DWORD dst_unused:UNUSED_PAD src0_sel:WORD_1 src1_sel:DWORD
	v_add3_u32 v17, v63, v17, s47
	v_add3_u32 v60, v62, v60, s47
	v_add3_u32 v13, v61, v13, s47
	v_and_b32_e32 v17, 0xffff0000, v17
	v_and_b32_e32 v60, 0xffff0000, v60
	v_or_b32_sdwa v61, v17, v13 dst_sel:DWORD dst_unused:UNUSED_PAD src0_sel:DWORD src1_sel:WORD_1
	v_or_b32_sdwa v60, v60, v15 dst_sel:DWORD dst_unused:UNUSED_PAD src0_sel:DWORD src1_sel:WORD_1
	v_mov_b32_e32 v13, v1
	global_store_dwordx2 v[8:9], v[60:61], off
	v_lshl_add_u64 v[68:69], v[56:57], 0, v[12:13]
	v_lshl_add_u64 v[72:73], v[54:55], 0, v[12:13]
	v_pk_mul_f32 v[76:77], v[88:89], v[84:85] op_sel_hi:[0,1]
	v_pk_mul_f32 v[78:79], v[88:89], v[86:87] op_sel_hi:[0,1]
	v_mov_b32_e32 v15, v1
	s_waitcnt lgkmcnt(0)
	v_mov_b32_e32 v60, v92
	v_mov_b32_e32 v61, v93
	v_mov_b32_e32 v62, v94
	v_mov_b32_e32 v63, v95
	v_mov_b32_e32 v68, v96
	v_mov_b32_e32 v69, v97
	v_mov_b32_e32 v70, v98
	v_mov_b32_e32 v71, v99
	v_mov_b32_e32 v72, v100
	v_mov_b32_e32 v73, v101
	v_mov_b32_e32 v74, v102
	v_mov_b32_e32 v75, v103
	v_mov_b32_e32 v80, v60
	v_mov_b32_e32 v81, v62
	v_mov_b32_e32 v82, v68
	v_mov_b32_e32 v83, v70
	v_mov_b32_e32 v62, v61
	v_mov_b32_e32 v70, v69
	v_mov_b32_e32 v84, v72
	v_mov_b32_e32 v85, v74
	v_mov_b32_e32 v74, v73
	v_pk_mul_f32 v[60:61], v[76:77], v[80:81]
	v_pk_add_f32 v[68:69], v[82:83], 1.0 op_sel_hi:[1,0]
	v_pk_mul_f32 v[62:63], v[78:79], v[62:63]
	v_pk_add_f32 v[70:71], v[70:71], 1.0 op_sel_hi:[1,0]
	v_pk_fma_f32 v[60:61], v[60:61], v[68:69], v[84:85]
	v_pk_fma_f32 v[62:63], v[62:63], v[70:71], v[74:75]
	v_and_b32_sdwa v17, v61, v65 dst_sel:DWORD dst_unused:UNUSED_PAD src0_sel:WORD_1 src1_sel:DWORD
	v_and_b32_sdwa v69, v63, v65 dst_sel:DWORD dst_unused:UNUSED_PAD src0_sel:WORD_1 src1_sel:DWORD
	v_and_b32_sdwa v70, v62, v65 dst_sel:DWORD dst_unused:UNUSED_PAD src0_sel:WORD_1 src1_sel:DWORD
	v_and_b32_sdwa v68, v60, v65 dst_sel:DWORD dst_unused:UNUSED_PAD src0_sel:WORD_1 src1_sel:DWORD
	v_add3_u32 v17, v61, v17, s47
	v_add3_u32 v61, v63, v69, s47
	v_add3_u32 v62, v62, v70, s47
	v_add3_u32 v60, v60, v68, s47
	v_and_b32_e32 v61, 0xffff0000, v61
	v_and_b32_e32 v62, 0xffff0000, v62
	v_or_b32_sdwa v61, v61, v17 dst_sel:DWORD dst_unused:UNUSED_PAD src0_sel:DWORD src1_sel:WORD_1
	v_or_b32_sdwa v60, v62, v60 dst_sel:DWORD dst_unused:UNUSED_PAD src0_sel:DWORD src1_sel:WORD_1
	global_store_dwordx2 v[8:9], v[60:61], off offset:512
	v_lshl_add_u64 v[68:69], v[56:57], 0, v[14:15]
	v_lshl_add_u64 v[72:73], v[54:55], 0, v[14:15]
	v_mov_b32_e32 v78, v48
	v_mov_b32_e32 v79, v50
	v_mov_b32_e32 v76, v58
	v_mov_b32_e32 v77, v52
	v_pk_mul_f32 v[78:79], v[88:89], v[78:79] op_sel_hi:[0,1]
	v_pk_mul_f32 v[76:77], v[88:89], v[76:77] op_sel_hi:[0,1]
	v_mov_b32_e32 v17, v1
	v_lshl_add_u64 v[56:57], v[56:57], 0, v[16:17]
	v_lshl_add_u64 v[54:55], v[54:55], 0, v[16:17]
	s_waitcnt lgkmcnt(0)
	v_mov_b32_e32 v60, v104
	v_mov_b32_e32 v61, v105
	v_mov_b32_e32 v62, v106
	v_mov_b32_e32 v63, v107
	v_mov_b32_e32 v68, v108
	v_mov_b32_e32 v69, v109
	v_mov_b32_e32 v70, v110
	v_mov_b32_e32 v71, v111
	v_mov_b32_e32 v72, v112
	v_mov_b32_e32 v73, v113
	v_mov_b32_e32 v74, v114
	v_mov_b32_e32 v75, v115
	v_mov_b32_e32 v81, v62
	v_mov_b32_e32 v62, v61
	v_mov_b32_e32 v83, v70
	v_mov_b32_e32 v70, v69
	v_mov_b32_e32 v80, v60
	v_mov_b32_e32 v82, v68
	v_mov_b32_e32 v85, v74
	v_mov_b32_e32 v74, v73
	v_pk_mul_f32 v[62:63], v[78:79], v[62:63]
	v_pk_add_f32 v[70:71], v[70:71], 1.0 op_sel_hi:[1,0]
	v_mov_b32_e32 v84, v72
	v_pk_mul_f32 v[60:61], v[76:77], v[80:81]
	v_pk_add_f32 v[68:69], v[82:83], 1.0 op_sel_hi:[1,0]
	v_pk_fma_f32 v[62:63], v[62:63], v[70:71], v[74:75]
	v_pk_fma_f32 v[60:61], v[60:61], v[68:69], v[84:85]
	v_and_b32_sdwa v52, v63, v65 dst_sel:DWORD dst_unused:UNUSED_PAD src0_sel:WORD_1 src1_sel:DWORD
	v_and_b32_sdwa v58, v62, v65 dst_sel:DWORD dst_unused:UNUSED_PAD src0_sel:WORD_1 src1_sel:DWORD
	v_and_b32_sdwa v48, v61, v65 dst_sel:DWORD dst_unused:UNUSED_PAD src0_sel:WORD_1 src1_sel:DWORD
	v_and_b32_sdwa v50, v60, v65 dst_sel:DWORD dst_unused:UNUSED_PAD src0_sel:WORD_1 src1_sel:DWORD
	v_add3_u32 v52, v63, v52, s47
	v_add3_u32 v58, v62, v58, s47
	v_add3_u32 v50, v60, v50, s47
	v_add3_u32 v48, v61, v48, s47
	v_and_b32_e32 v52, 0xffff0000, v52
	v_and_b32_e32 v58, 0xffff0000, v58
	v_or_b32_sdwa v61, v52, v48 dst_sel:DWORD dst_unused:UNUSED_PAD src0_sel:DWORD src1_sel:WORD_1
	v_or_b32_sdwa v60, v58, v50 dst_sel:DWORD dst_unused:UNUSED_PAD src0_sel:DWORD src1_sel:WORD_1
	global_store_dwordx2 v[8:9], v[60:61], off offset:1024
	v_mov_b32_e32 v52, v59
	v_mov_b32_e32 v50, v49
	v_pk_mul_f32 v[48:49], v[88:89], v[52:53] op_sel_hi:[0,1]
	v_pk_mul_f32 v[50:51], v[88:89], v[50:51] op_sel_hi:[0,1]
	s_waitcnt lgkmcnt(0)
	v_mov_b32_e32 v60, v116
	v_mov_b32_e32 v61, v117
	v_mov_b32_e32 v62, v118
	v_mov_b32_e32 v63, v119
	v_mov_b32_e32 v68, v120
	v_mov_b32_e32 v69, v121
	v_mov_b32_e32 v70, v122
	v_mov_b32_e32 v71, v123
	v_mov_b32_e32 v54, v124
	v_mov_b32_e32 v55, v125
	v_mov_b32_e32 v56, v126
	v_mov_b32_e32 v57, v127
	v_mov_b32_e32 v53, v62
	v_mov_b32_e32 v62, v61
	v_mov_b32_e32 v59, v70
	v_mov_b32_e32 v70, v69
	v_mov_b32_e32 v52, v60
	v_mov_b32_e32 v58, v68
	v_mov_b32_e32 v72, v54
	v_mov_b32_e32 v73, v56
	v_mov_b32_e32 v56, v55
	v_pk_mul_f32 v[50:51], v[50:51], v[62:63]
	v_pk_add_f32 v[54:55], v[70:71], 1.0 op_sel_hi:[1,0]
	v_pk_mul_f32 v[48:49], v[48:49], v[52:53]
	v_pk_add_f32 v[52:53], v[58:59], 1.0 op_sel_hi:[1,0]
	v_pk_fma_f32 v[50:51], v[50:51], v[54:55], v[56:57]
	v_pk_fma_f32 v[48:49], v[48:49], v[52:53], v[72:73]
	v_and_b32_sdwa v54, v51, v65 dst_sel:DWORD dst_unused:UNUSED_PAD src0_sel:WORD_1 src1_sel:DWORD
	v_and_b32_sdwa v55, v50, v65 dst_sel:DWORD dst_unused:UNUSED_PAD src0_sel:WORD_1 src1_sel:DWORD
	v_and_b32_sdwa v52, v49, v65 dst_sel:DWORD dst_unused:UNUSED_PAD src0_sel:WORD_1 src1_sel:DWORD
	v_and_b32_sdwa v53, v48, v65 dst_sel:DWORD dst_unused:UNUSED_PAD src0_sel:WORD_1 src1_sel:DWORD
	v_add3_u32 v51, v51, v54, s47
	v_add3_u32 v50, v50, v55, s47
	v_add3_u32 v48, v48, v53, s47
	v_add3_u32 v49, v49, v52, s47
	v_and_b32_e32 v51, 0xffff0000, v51
	v_and_b32_e32 v50, 0xffff0000, v50
	v_or_b32_sdwa v49, v51, v49 dst_sel:DWORD dst_unused:UNUSED_PAD src0_sel:DWORD src1_sel:WORD_1
	v_or_b32_sdwa v48, v50, v48 dst_sel:DWORD dst_unused:UNUSED_PAD src0_sel:DWORD src1_sel:WORD_1
	global_store_dwordx2 v[8:9], v[48:49], off offset:1536
	s_and_saveexec_b64 s[6:7], s[0:1]
	s_cbranch_execz .LBB0_908
	v_cndmask_b32_e64 v39, v39, 16, s[4:5]
	v_mul_hi_i32_i24_e32 v53, 0x6000, v39
	v_mul_i32_i24_e32 v52, 0x6000, v39
	v_lshl_add_u64 v[52:53], s[12:13], 0, v[52:53]
	v_lshl_add_u64 v[60:61], v[52:53], 0, s[22:23]
	global_load_dwordx4 v[48:51], v[4:5], off
	v_lshl_add_u64 v[62:63], v[52:53], 0, s[24:25]
	v_lshl_add_u64 v[52:53], v[60:61], 0, v[0:1]
	global_load_dwordx4 v[52:55], v[52:53], off
	v_lshl_add_u64 v[56:57], v[62:63], 0, v[0:1]
	global_load_dwordx4 v[56:59], v[56:57], off
	global_load_dwordx4 v[92:95], v[4:5], off offset:1024
	v_mov_b32_e32 v128, v12
	v_mov_b32_e32 v129, v1
	v_lshl_add_u64 v[130:131], v[60:61], 0, v[128:129]
	global_load_dwordx4 v[96:99], v[130:131], off
	v_mov_b32_e32 v128, v12
	v_mov_b32_e32 v129, v1
	v_lshl_add_u64 v[130:131], v[62:63], 0, v[128:129]
	global_load_dwordx4 v[100:103], v[130:131], off
	global_load_dwordx4 v[104:107], v[4:5], off offset:2048
	v_mov_b32_e32 v128, v14
	v_mov_b32_e32 v129, v1
	v_lshl_add_u64 v[130:131], v[60:61], 0, v[128:129]
	global_load_dwordx4 v[108:111], v[130:131], off
	v_mov_b32_e32 v128, v14
	v_mov_b32_e32 v129, v1
	v_lshl_add_u64 v[130:131], v[62:63], 0, v[128:129]
	global_load_dwordx4 v[112:115], v[130:131], off
	global_load_dwordx4 v[116:119], v[4:5], off offset:3072
	v_mov_b32_e32 v128, v16
	v_mov_b32_e32 v129, v1
	v_lshl_add_u64 v[130:131], v[60:61], 0, v[128:129]
	global_load_dwordx4 v[120:123], v[130:131], off
	v_mov_b32_e32 v128, v16
	v_mov_b32_e32 v129, v1
	v_lshl_add_u64 v[130:131], v[62:63], 0, v[128:129]
	global_load_dwordx4 v[124:127], v[130:131], off
	v_lshlrev_b32_e32 v68, 16, v46
	v_and_b32_e32 v46, 0xffff0000, v46
	v_and_b32_e32 v72, 0xffff0000, v44
	v_lshlrev_b32_e32 v70, 16, v44
	v_lshlrev_b32_e32 v75, 16, v42
	v_and_b32_e32 v77, 0xffff0000, v42
	v_lshlrev_b32_e32 v79, 16, v43
	v_and_b32_e32 v81, 0xffff0000, v43
	v_mov_b32_e32 v42, v46
	v_mov_b32_e32 v43, v72
	v_lshlrev_b32_e32 v69, 16, v47
	v_lshlrev_b32_e32 v71, 16, v45
	v_lshlrev_b32_e32 v74, 16, v40
	v_and_b32_e32 v76, 0xffff0000, v40
	v_lshlrev_b32_e32 v78, 16, v41
	v_and_b32_e32 v80, 0xffff0000, v41
	v_mov_b32_e32 v40, v68
	v_mov_b32_e32 v41, v70
	v_pk_mul_f32 v[42:43], v[42:43], v[42:43]
	v_and_b32_e32 v47, 0xffff0000, v47
	v_and_b32_e32 v73, 0xffff0000, v45
	v_mov_b32_e32 v44, v69
	v_mov_b32_e32 v45, v71
	v_pk_mul_f32 v[84:85], v[76:77], v[76:77]
	v_pk_fma_f32 v[40:41], v[40:41], v[40:41], v[42:43]
	v_mov_b32_e32 v82, v47
	v_mov_b32_e32 v83, v73
	v_pk_fma_f32 v[84:85], v[74:75], v[74:75], v[84:85]
	v_pk_fma_f32 v[40:41], v[44:45], v[44:45], v[40:41]
	v_pk_fma_f32 v[42:43], v[78:79], v[78:79], v[84:85]
	v_pk_fma_f32 v[40:41], v[82:83], v[82:83], v[40:41]
	v_pk_fma_f32 v[42:43], v[80:81], v[80:81], v[42:43]
	v_add_f32_e32 v39, v40, v41
	v_add_f32_e32 v39, v39, v42
	v_add_f32_e32 v39, v39, v43
	s_waitcnt vmcnt(0) lgkmcnt(0)
	v_mov_b32_e32 v44, v48
	v_add_f32_dpp v39, v39, v39 quad_perm:[1,0,3,2] row_mask:0xf bank_mask:0xf bound_ctrl:1
	v_mov_b32_e32 v45, v50
	v_mov_b32_e32 v50, v49
	v_add_f32_dpp v39, v39, v39 quad_perm:[2,3,0,1] row_mask:0xf bank_mask:0xf bound_ctrl:1
	s_nop 1
	v_add_f32_dpp v39, v39, v39 row_half_mirror row_mask:0xf bank_mask:0xf bound_ctrl:1
	s_nop 1
	v_add_f32_dpp v39, v39, v39 row_mirror row_mask:0xf bank_mask:0xf bound_ctrl:1
	s_nop 0
	v_readlane_b32 s4, v39, 16
	v_readlane_b32 s5, v39, 48
	v_readlane_b32 s0, v39, 0
	v_readlane_b32 s1, v39, 32
	v_mov_b32_e32 v40, s4
	v_mov_b32_e32 v41, s5
	v_pk_add_f32 v[40:41], s[0:1], v[40:41]
	s_nop 0
	v_add_f32_e32 v39, v40, v41
	v_fmamk_f32 v39, v39, 0x3a800000, v64
	v_mul_f32_e32 v40, 0x4b800000, v39
	v_cmp_gt_f32_e64 s[0:1], s46, v39
	s_nop 1
	v_cndmask_b32_e64 v39, v39, v40, s[0:1]
	v_rsq_f32_e32 v40, v39
	v_ashrrev_i32_e32 v39, 31, v38
	v_lshlrev_b64 v[38:39], 11, v[38:39]
	v_mul_f32_e32 v41, 0x45800000, v40
	v_cndmask_b32_e64 v82, v40, v41, s[0:1]
	v_pk_mul_f32 v[40:41], v[82:83], v[68:69] op_sel_hi:[0,1]
	v_pk_mul_f32 v[42:43], v[82:83], v[46:47] op_sel_hi:[0,1]
	v_pk_mul_f32 v[40:41], v[44:45], v[40:41]
	v_mov_b32_e32 v45, v54
	v_mov_b32_e32 v54, v53
	v_pk_mul_f32 v[42:43], v[50:51], v[42:43]
	v_mov_b32_e32 v44, v52
	v_mov_b32_e32 v47, v58
	v_mov_b32_e32 v58, v57
	v_pk_add_f32 v[48:49], v[54:55], 1.0 op_sel_hi:[1,0]
	v_mov_b32_e32 v46, v56
	v_pk_add_f32 v[44:45], v[44:45], 1.0 op_sel_hi:[1,0]
	v_pk_fma_f32 v[42:43], v[48:49], v[42:43], v[58:59]
	v_pk_fma_f32 v[40:41], v[44:45], v[40:41], v[46:47]
	v_and_b32_sdwa v46, v43, v65 dst_sel:DWORD dst_unused:UNUSED_PAD src0_sel:WORD_1 src1_sel:DWORD
	v_and_b32_sdwa v47, v42, v65 dst_sel:DWORD dst_unused:UNUSED_PAD src0_sel:WORD_1 src1_sel:DWORD
	v_and_b32_sdwa v44, v41, v65 dst_sel:DWORD dst_unused:UNUSED_PAD src0_sel:WORD_1 src1_sel:DWORD
	v_and_b32_sdwa v45, v40, v65 dst_sel:DWORD dst_unused:UNUSED_PAD src0_sel:WORD_1 src1_sel:DWORD
	v_add3_u32 v43, v43, v46, s47
	v_add3_u32 v42, v42, v47, s47
	v_add3_u32 v40, v40, v45, s47
	v_add3_u32 v41, v41, v44, s47
	v_and_b32_e32 v43, 0xffff0000, v43
	v_and_b32_e32 v42, 0xffff0000, v42
	v_or_b32_sdwa v41, v43, v41 dst_sel:DWORD dst_unused:UNUSED_PAD src0_sel:DWORD src1_sel:WORD_1
	v_or_b32_sdwa v40, v42, v40 dst_sel:DWORD dst_unused:UNUSED_PAD src0_sel:DWORD src1_sel:WORD_1
	v_lshl_add_u64 v[50:51], v[6:7], 0, v[38:39]
	global_store_dwordx2 v[50:51], v[40:41], off
	v_lshl_add_u64 v[42:43], v[60:61], 0, v[12:13]
	v_lshl_add_u64 v[46:47], v[62:63], 0, v[12:13]
	v_pk_mul_f32 v[52:53], v[82:83], v[70:71] op_sel_hi:[0,1]
	v_pk_mul_f32 v[54:55], v[82:83], v[72:73] op_sel_hi:[0,1]
	v_cmp_gt_i32_e64 s[0:1], s39, v66
	s_waitcnt lgkmcnt(0)
	v_mov_b32_e32 v38, v92
	v_mov_b32_e32 v39, v93
	v_mov_b32_e32 v40, v94
	v_mov_b32_e32 v41, v95
	v_mov_b32_e32 v42, v96
	v_mov_b32_e32 v43, v97
	v_mov_b32_e32 v44, v98
	v_mov_b32_e32 v45, v99
	v_mov_b32_e32 v46, v100
	v_mov_b32_e32 v47, v101
	v_mov_b32_e32 v48, v102
	v_mov_b32_e32 v49, v103
	v_mov_b32_e32 v56, v38
	v_mov_b32_e32 v57, v40
	v_mov_b32_e32 v58, v42
	v_mov_b32_e32 v59, v44
	v_mov_b32_e32 v40, v39
	v_mov_b32_e32 v44, v43
	v_mov_b32_e32 v68, v46
	v_mov_b32_e32 v69, v48
	v_mov_b32_e32 v48, v47
	v_pk_mul_f32 v[38:39], v[52:53], v[56:57]
	v_pk_add_f32 v[42:43], v[58:59], 1.0 op_sel_hi:[1,0]
	v_pk_mul_f32 v[40:41], v[54:55], v[40:41]
	v_pk_add_f32 v[44:45], v[44:45], 1.0 op_sel_hi:[1,0]
	v_pk_fma_f32 v[38:39], v[38:39], v[42:43], v[68:69]
	v_pk_fma_f32 v[40:41], v[40:41], v[44:45], v[48:49]
	v_and_b32_sdwa v13, v39, v65 dst_sel:DWORD dst_unused:UNUSED_PAD src0_sel:WORD_1 src1_sel:DWORD
	v_and_b32_sdwa v43, v41, v65 dst_sel:DWORD dst_unused:UNUSED_PAD src0_sel:WORD_1 src1_sel:DWORD
	v_and_b32_sdwa v44, v40, v65 dst_sel:DWORD dst_unused:UNUSED_PAD src0_sel:WORD_1 src1_sel:DWORD
	v_and_b32_sdwa v42, v38, v65 dst_sel:DWORD dst_unused:UNUSED_PAD src0_sel:WORD_1 src1_sel:DWORD
	v_add3_u32 v13, v39, v13, s47
	v_add3_u32 v39, v41, v43, s47
	v_add3_u32 v40, v40, v44, s47
	v_add3_u32 v38, v38, v42, s47
	v_and_b32_e32 v39, 0xffff0000, v39
	v_and_b32_e32 v40, 0xffff0000, v40
	v_or_b32_sdwa v39, v39, v13 dst_sel:DWORD dst_unused:UNUSED_PAD src0_sel:DWORD src1_sel:WORD_1
	v_or_b32_sdwa v38, v40, v38 dst_sel:DWORD dst_unused:UNUSED_PAD src0_sel:DWORD src1_sel:WORD_1
	global_store_dwordx2 v[50:51], v[38:39], off offset:512
	v_lshl_add_u64 v[42:43], v[60:61], 0, v[14:15]
	v_lshl_add_u64 v[46:47], v[62:63], 0, v[14:15]
	v_mov_b32_e32 v52, v74
	v_mov_b32_e32 v53, v78
	v_mov_b32_e32 v54, v76
	v_mov_b32_e32 v55, v80
	v_pk_mul_f32 v[52:53], v[82:83], v[52:53] op_sel_hi:[0,1]
	v_pk_mul_f32 v[54:55], v[82:83], v[54:55] op_sel_hi:[0,1]
	v_mov_b32_e32 v78, v75
	v_mov_b32_e32 v80, v77
	s_waitcnt lgkmcnt(0)
	v_mov_b32_e32 v38, v104
	v_mov_b32_e32 v39, v105
	v_mov_b32_e32 v40, v106
	v_mov_b32_e32 v41, v107
	v_mov_b32_e32 v42, v108
	v_mov_b32_e32 v43, v109
	v_mov_b32_e32 v44, v110
	v_mov_b32_e32 v45, v111
	v_mov_b32_e32 v46, v112
	v_mov_b32_e32 v47, v113
	v_mov_b32_e32 v48, v114
	v_mov_b32_e32 v49, v115
	v_mov_b32_e32 v56, v38
	v_mov_b32_e32 v57, v40
	v_mov_b32_e32 v58, v42
	v_mov_b32_e32 v59, v44
	v_mov_b32_e32 v40, v39
	v_mov_b32_e32 v44, v43
	v_mov_b32_e32 v68, v46
	v_mov_b32_e32 v69, v48
	v_mov_b32_e32 v48, v47
	v_pk_mul_f32 v[38:39], v[52:53], v[56:57]
	v_pk_add_f32 v[42:43], v[58:59], 1.0 op_sel_hi:[1,0]
	v_pk_mul_f32 v[40:41], v[54:55], v[40:41]
	v_pk_add_f32 v[44:45], v[44:45], 1.0 op_sel_hi:[1,0]
	v_pk_fma_f32 v[38:39], v[38:39], v[42:43], v[68:69]
	v_pk_fma_f32 v[40:41], v[40:41], v[44:45], v[48:49]
	v_and_b32_sdwa v13, v39, v65 dst_sel:DWORD dst_unused:UNUSED_PAD src0_sel:WORD_1 src1_sel:DWORD
	v_and_b32_sdwa v15, v38, v65 dst_sel:DWORD dst_unused:UNUSED_PAD src0_sel:WORD_1 src1_sel:DWORD
	v_and_b32_sdwa v42, v41, v65 dst_sel:DWORD dst_unused:UNUSED_PAD src0_sel:WORD_1 src1_sel:DWORD
	v_and_b32_sdwa v43, v40, v65 dst_sel:DWORD dst_unused:UNUSED_PAD src0_sel:WORD_1 src1_sel:DWORD
	v_add3_u32 v15, v38, v15, s47
	v_add3_u32 v13, v39, v13, s47
	v_add3_u32 v38, v41, v42, s47
	v_add3_u32 v39, v40, v43, s47
	v_and_b32_e32 v38, 0xffff0000, v38
	v_and_b32_e32 v40, 0xffff0000, v39
	v_or_b32_sdwa v39, v38, v13 dst_sel:DWORD dst_unused:UNUSED_PAD src0_sel:DWORD src1_sel:WORD_1
	v_or_b32_sdwa v38, v40, v15 dst_sel:DWORD dst_unused:UNUSED_PAD src0_sel:DWORD src1_sel:WORD_1
	global_store_dwordx2 v[50:51], v[38:39], off offset:1024
	v_lshl_add_u64 v[42:43], v[60:61], 0, v[16:17]
	v_lshl_add_u64 v[46:47], v[62:63], 0, v[16:17]
	v_pk_mul_f32 v[52:53], v[82:83], v[78:79] op_sel_hi:[0,1]
	v_pk_mul_f32 v[54:55], v[82:83], v[80:81] op_sel_hi:[0,1]
	s_waitcnt lgkmcnt(0)
	v_mov_b32_e32 v38, v116
	v_mov_b32_e32 v39, v117
	v_mov_b32_e32 v40, v118
	v_mov_b32_e32 v41, v119
	v_mov_b32_e32 v42, v120
	v_mov_b32_e32 v43, v121
	v_mov_b32_e32 v44, v122
	v_mov_b32_e32 v45, v123
	v_mov_b32_e32 v46, v124
	v_mov_b32_e32 v47, v125
	v_mov_b32_e32 v48, v126
	v_mov_b32_e32 v49, v127
	v_mov_b32_e32 v56, v38
	v_mov_b32_e32 v57, v40
	v_mov_b32_e32 v58, v42
	v_mov_b32_e32 v59, v44
	v_mov_b32_e32 v40, v39
	v_mov_b32_e32 v44, v43
	v_mov_b32_e32 v60, v46
	v_mov_b32_e32 v61, v48
	v_mov_b32_e32 v48, v47
	v_pk_mul_f32 v[38:39], v[52:53], v[56:57]
	v_pk_add_f32 v[42:43], v[58:59], 1.0 op_sel_hi:[1,0]
	v_pk_mul_f32 v[40:41], v[54:55], v[40:41]
	v_pk_add_f32 v[44:45], v[44:45], 1.0 op_sel_hi:[1,0]
	v_pk_fma_f32 v[38:39], v[38:39], v[42:43], v[60:61]
	v_pk_fma_f32 v[40:41], v[40:41], v[44:45], v[48:49]
	v_and_b32_sdwa v15, v38, v65 dst_sel:DWORD dst_unused:UNUSED_PAD src0_sel:WORD_1 src1_sel:DWORD
	v_and_b32_sdwa v17, v41, v65 dst_sel:DWORD dst_unused:UNUSED_PAD src0_sel:WORD_1 src1_sel:DWORD
	v_and_b32_sdwa v42, v40, v65 dst_sel:DWORD dst_unused:UNUSED_PAD src0_sel:WORD_1 src1_sel:DWORD
	v_and_b32_sdwa v13, v39, v65 dst_sel:DWORD dst_unused:UNUSED_PAD src0_sel:WORD_1 src1_sel:DWORD
	v_add3_u32 v15, v38, v15, s47
	v_add3_u32 v17, v41, v17, s47
	v_add3_u32 v38, v40, v42, s47
	v_add3_u32 v13, v39, v13, s47
	v_and_b32_e32 v17, 0xffff0000, v17
	v_and_b32_e32 v38, 0xffff0000, v38
	v_or_b32_sdwa v39, v17, v13 dst_sel:DWORD dst_unused:UNUSED_PAD src0_sel:DWORD src1_sel:WORD_1
	v_or_b32_sdwa v38, v38, v15 dst_sel:DWORD dst_unused:UNUSED_PAD src0_sel:DWORD src1_sel:WORD_1
	global_store_dwordx2 v[50:51], v[38:39], off offset:1536
	s_and_b64 exec, exec, s[0:1]
	s_cbranch_execz .LBB0_908
	v_cndmask_b32_e64 v13, v29, 16, s[2:3]
	v_mul_hi_i32_i24_e32 v39, 0x6000, v13
	v_mul_i32_i24_e32 v38, 0x6000, v13
	v_lshl_add_u64 v[38:39], s[12:13], 0, v[38:39]
	v_lshl_add_u64 v[40:41], v[38:39], 0, s[22:23]
	global_load_dwordx4 v[44:47], v[4:5], off
	v_lshl_add_u64 v[38:39], v[38:39], 0, s[24:25]
	v_lshl_add_u64 v[42:43], v[40:41], 0, v[0:1]
	global_load_dwordx4 v[48:51], v[42:43], off
	v_lshl_add_u64 v[42:43], v[38:39], 0, v[0:1]
	global_load_dwordx4 v[52:55], v[42:43], off
	global_load_dwordx4 v[92:95], v[4:5], off offset:1024
	v_mov_b32_e32 v128, v12
	v_mov_b32_e32 v129, v1
	v_lshl_add_u64 v[130:131], v[40:41], 0, v[128:129]
	global_load_dwordx4 v[96:99], v[130:131], off
	v_mov_b32_e32 v128, v12
	v_mov_b32_e32 v129, v1
	v_lshl_add_u64 v[130:131], v[38:39], 0, v[128:129]
	global_load_dwordx4 v[100:103], v[130:131], off
	global_load_dwordx4 v[104:107], v[4:5], off offset:2048
	v_mov_b32_e32 v128, v14
	v_mov_b32_e32 v129, v1
	v_lshl_add_u64 v[130:131], v[40:41], 0, v[128:129]
	global_load_dwordx4 v[108:111], v[130:131], off
	v_mov_b32_e32 v128, v14
	v_mov_b32_e32 v129, v1
	v_lshl_add_u64 v[130:131], v[38:39], 0, v[128:129]
	global_load_dwordx4 v[112:115], v[130:131], off
	global_load_dwordx4 v[116:119], v[4:5], off offset:3072
	v_mov_b32_e32 v128, v16
	v_mov_b32_e32 v129, v1
	v_lshl_add_u64 v[130:131], v[40:41], 0, v[128:129]
	global_load_dwordx4 v[120:123], v[130:131], off
	v_mov_b32_e32 v128, v16
	v_mov_b32_e32 v129, v1
	v_lshl_add_u64 v[130:131], v[38:39], 0, v[128:129]
	global_load_dwordx4 v[124:127], v[130:131], off
	v_and_b32_e32 v58, 0xffff0000, v36
	v_and_b32_e32 v62, 0xffff0000, v34
	v_lshlrev_b32_e32 v56, 16, v36
	v_lshlrev_b32_e32 v60, 16, v34
	v_mov_b32_e32 v66, v58
	v_mov_b32_e32 v67, v62
	v_lshlrev_b32_e32 v57, 16, v37
	v_lshlrev_b32_e32 v61, 16, v35
	v_and_b32_e32 v63, 0xffff0000, v35
	v_lshlrev_b32_e32 v43, 16, v32
	v_lshlrev_b32_e32 v42, 16, v30
	v_and_b32_e32 v35, 0xffff0000, v32
	v_and_b32_e32 v34, 0xffff0000, v30
	v_lshlrev_b32_e32 v36, 16, v31
	v_and_b32_e32 v32, 0xffff0000, v31
	v_mov_b32_e32 v30, v56
	v_mov_b32_e32 v31, v60
	v_pk_mul_f32 v[66:67], v[66:67], v[66:67]
	v_and_b32_e32 v59, 0xffff0000, v37
	v_mov_b32_e32 v68, v57
	v_mov_b32_e32 v69, v61
	v_pk_mul_f32 v[72:73], v[34:35], v[34:35]
	v_pk_fma_f32 v[30:31], v[30:31], v[30:31], v[66:67]
	v_lshlrev_b32_e32 v37, 16, v33
	v_mov_b32_e32 v70, v59
	v_mov_b32_e32 v71, v63
	v_pk_fma_f32 v[72:73], v[42:43], v[42:43], v[72:73]
	v_pk_fma_f32 v[30:31], v[68:69], v[68:69], v[30:31]
	v_and_b32_e32 v33, 0xffff0000, v33
	v_pk_fma_f32 v[66:67], v[36:37], v[36:37], v[72:73]
	v_pk_fma_f32 v[30:31], v[70:71], v[70:71], v[30:31]
	v_pk_fma_f32 v[66:67], v[32:33], v[32:33], v[66:67]
	v_add_f32_e32 v13, v30, v31
	v_add_f32_e32 v13, v13, v66
	v_add_f32_e32 v13, v13, v67
	v_ashrrev_i32_e32 v29, 31, v28
	v_lshlrev_b64 v[28:29], 11, v[28:29]
	v_add_f32_dpp v13, v13, v13 quad_perm:[1,0,3,2] row_mask:0xf bank_mask:0xf bound_ctrl:1
	s_nop 1
	v_add_f32_dpp v13, v13, v13 quad_perm:[2,3,0,1] row_mask:0xf bank_mask:0xf bound_ctrl:1
	s_nop 1
	v_add_f32_dpp v13, v13, v13 row_half_mirror row_mask:0xf bank_mask:0xf bound_ctrl:1
	s_nop 1
	v_add_f32_dpp v13, v13, v13 row_mirror row_mask:0xf bank_mask:0xf bound_ctrl:1
	s_nop 0
	v_readlane_b32 s2, v13, 16
	v_readlane_b32 s3, v13, 48
	v_readlane_b32 s0, v13, 0
	v_readlane_b32 s1, v13, 32
	v_mov_b32_e32 v30, s2
	v_mov_b32_e32 v31, s3
	v_pk_add_f32 v[30:31], s[0:1], v[30:31]
	s_nop 0
	v_add_f32_e32 v13, v30, v31
	v_fmamk_f32 v13, v13, 0x3a800000, v64
	v_mul_f32_e32 v15, 0x4b800000, v13
	v_cmp_gt_f32_e64 s[0:1], s46, v13
	s_nop 1
	v_cndmask_b32_e64 v13, v13, v15, s[0:1]
	v_rsq_f32_e32 v13, v13
	s_nop 0
	v_mul_f32_e32 v15, 0x45800000, v13
	v_cndmask_b32_e64 v66, v13, v15, s[0:1]
	v_pk_mul_f32 v[30:31], v[66:67], v[56:57] op_sel_hi:[0,1]
	v_pk_mul_f32 v[56:57], v[66:67], v[58:59] op_sel_hi:[0,1]
	v_cmp_gt_i32_e64 s[0:1], s39, v19
	s_waitcnt vmcnt(0) lgkmcnt(0)
	v_mov_b32_e32 v59, v46
	v_mov_b32_e32 v46, v45
	v_mov_b32_e32 v58, v44
	v_pk_mul_f32 v[44:45], v[46:47], v[56:57]
	v_mov_b32_e32 v46, v48
	v_mov_b32_e32 v47, v50
	v_mov_b32_e32 v50, v49
	v_pk_mul_f32 v[30:31], v[58:59], v[30:31]
	v_mov_b32_e32 v56, v52
	v_mov_b32_e32 v57, v54
	v_mov_b32_e32 v54, v53
	v_pk_add_f32 v[46:47], v[46:47], 1.0 op_sel_hi:[1,0]
	v_pk_add_f32 v[48:49], v[50:51], 1.0 op_sel_hi:[1,0]
	v_pk_fma_f32 v[30:31], v[46:47], v[30:31], v[56:57]
	v_pk_fma_f32 v[44:45], v[48:49], v[44:45], v[54:55]
	v_and_b32_sdwa v15, v30, v65 dst_sel:DWORD dst_unused:UNUSED_PAD src0_sel:WORD_1 src1_sel:DWORD
	v_and_b32_sdwa v17, v45, v65 dst_sel:DWORD dst_unused:UNUSED_PAD src0_sel:WORD_1 src1_sel:DWORD
	v_and_b32_sdwa v46, v44, v65 dst_sel:DWORD dst_unused:UNUSED_PAD src0_sel:WORD_1 src1_sel:DWORD
	v_and_b32_sdwa v13, v31, v65 dst_sel:DWORD dst_unused:UNUSED_PAD src0_sel:WORD_1 src1_sel:DWORD
	v_add3_u32 v15, v30, v15, s47
	v_add3_u32 v17, v45, v17, s47
	v_add3_u32 v30, v44, v46, s47
	v_add3_u32 v13, v31, v13, s47
	v_and_b32_e32 v17, 0xffff0000, v17
	v_and_b32_e32 v30, 0xffff0000, v30
	v_or_b32_sdwa v31, v17, v13 dst_sel:DWORD dst_unused:UNUSED_PAD src0_sel:DWORD src1_sel:WORD_1
	v_or_b32_sdwa v30, v30, v15 dst_sel:DWORD dst_unused:UNUSED_PAD src0_sel:DWORD src1_sel:WORD_1
	v_lshl_add_u64 v[52:53], v[6:7], 0, v[28:29]
	v_mov_b32_e32 v13, v1
	global_store_dwordx2 v[52:53], v[30:31], off
	v_lshl_add_u64 v[44:45], v[40:41], 0, v[12:13]
	v_lshl_add_u64 v[48:49], v[38:39], 0, v[12:13]
	v_pk_mul_f32 v[54:55], v[66:67], v[60:61] op_sel_hi:[0,1]
	v_pk_mul_f32 v[56:57], v[66:67], v[62:63] op_sel_hi:[0,1]
	v_mov_b32_e32 v15, v1
	s_waitcnt lgkmcnt(0)
	v_mov_b32_e32 v28, v92
	v_mov_b32_e32 v29, v93
	v_mov_b32_e32 v30, v94
	v_mov_b32_e32 v31, v95
	v_mov_b32_e32 v44, v96
	v_mov_b32_e32 v45, v97
	v_mov_b32_e32 v46, v98
	v_mov_b32_e32 v47, v99
	v_mov_b32_e32 v48, v100
	v_mov_b32_e32 v49, v101
	v_mov_b32_e32 v50, v102
	v_mov_b32_e32 v51, v103
	v_mov_b32_e32 v58, v28
	v_mov_b32_e32 v59, v30
	v_mov_b32_e32 v60, v44
	v_mov_b32_e32 v61, v46
	v_mov_b32_e32 v30, v29
	v_mov_b32_e32 v46, v45
	v_mov_b32_e32 v62, v48
	v_mov_b32_e32 v63, v50
	v_mov_b32_e32 v50, v49
	v_pk_mul_f32 v[28:29], v[54:55], v[58:59]
	v_pk_add_f32 v[44:45], v[60:61], 1.0 op_sel_hi:[1,0]
	v_pk_mul_f32 v[30:31], v[56:57], v[30:31]
	v_pk_add_f32 v[46:47], v[46:47], 1.0 op_sel_hi:[1,0]
	v_pk_fma_f32 v[28:29], v[28:29], v[44:45], v[62:63]
	v_pk_fma_f32 v[30:31], v[30:31], v[46:47], v[50:51]
	v_and_b32_sdwa v17, v29, v65 dst_sel:DWORD dst_unused:UNUSED_PAD src0_sel:WORD_1 src1_sel:DWORD
	v_and_b32_sdwa v45, v31, v65 dst_sel:DWORD dst_unused:UNUSED_PAD src0_sel:WORD_1 src1_sel:DWORD
	v_and_b32_sdwa v46, v30, v65 dst_sel:DWORD dst_unused:UNUSED_PAD src0_sel:WORD_1 src1_sel:DWORD
	v_and_b32_sdwa v44, v28, v65 dst_sel:DWORD dst_unused:UNUSED_PAD src0_sel:WORD_1 src1_sel:DWORD
	v_add3_u32 v17, v29, v17, s47
	v_add3_u32 v29, v31, v45, s47
	v_add3_u32 v30, v30, v46, s47
	v_add3_u32 v28, v28, v44, s47
	v_and_b32_e32 v29, 0xffff0000, v29
	v_and_b32_e32 v30, 0xffff0000, v30
	v_or_b32_sdwa v29, v29, v17 dst_sel:DWORD dst_unused:UNUSED_PAD src0_sel:DWORD src1_sel:WORD_1
	v_or_b32_sdwa v28, v30, v28 dst_sel:DWORD dst_unused:UNUSED_PAD src0_sel:DWORD src1_sel:WORD_1
	global_store_dwordx2 v[52:53], v[28:29], off offset:512
	v_lshl_add_u64 v[44:45], v[40:41], 0, v[14:15]
	v_lshl_add_u64 v[48:49], v[38:39], 0, v[14:15]
	v_mov_b32_e32 v56, v34
	v_mov_b32_e32 v57, v32
	v_mov_b32_e32 v54, v42
	v_mov_b32_e32 v55, v36
	v_pk_mul_f32 v[56:57], v[66:67], v[56:57] op_sel_hi:[0,1]
	v_pk_mul_f32 v[54:55], v[66:67], v[54:55] op_sel_hi:[0,1]
	v_mov_b32_e32 v17, v1
	v_lshl_add_u64 v[40:41], v[40:41], 0, v[16:17]
	v_lshl_add_u64 v[38:39], v[38:39], 0, v[16:17]
	s_waitcnt lgkmcnt(0)
	v_mov_b32_e32 v28, v104
	v_mov_b32_e32 v29, v105
	v_mov_b32_e32 v30, v106
	v_mov_b32_e32 v31, v107
	v_mov_b32_e32 v44, v108
	v_mov_b32_e32 v45, v109
	v_mov_b32_e32 v46, v110
	v_mov_b32_e32 v47, v111
	v_mov_b32_e32 v48, v112
	v_mov_b32_e32 v49, v113
	v_mov_b32_e32 v50, v114
	v_mov_b32_e32 v51, v115
	v_mov_b32_e32 v59, v30
	v_mov_b32_e32 v30, v29
	v_mov_b32_e32 v61, v46
	v_mov_b32_e32 v46, v45
	v_mov_b32_e32 v58, v28
	v_mov_b32_e32 v60, v44
	v_mov_b32_e32 v63, v50
	v_mov_b32_e32 v50, v49
	v_pk_mul_f32 v[30:31], v[56:57], v[30:31]
	v_pk_add_f32 v[46:47], v[46:47], 1.0 op_sel_hi:[1,0]
	v_mov_b32_e32 v62, v48
	v_pk_mul_f32 v[28:29], v[54:55], v[58:59]
	v_pk_add_f32 v[44:45], v[60:61], 1.0 op_sel_hi:[1,0]
	v_pk_fma_f32 v[30:31], v[30:31], v[46:47], v[50:51]
	v_pk_fma_f32 v[28:29], v[28:29], v[44:45], v[62:63]
	v_and_b32_sdwa v36, v31, v65 dst_sel:DWORD dst_unused:UNUSED_PAD src0_sel:WORD_1 src1_sel:DWORD
	v_and_b32_sdwa v42, v30, v65 dst_sel:DWORD dst_unused:UNUSED_PAD src0_sel:WORD_1 src1_sel:DWORD
	v_and_b32_sdwa v32, v29, v65 dst_sel:DWORD dst_unused:UNUSED_PAD src0_sel:WORD_1 src1_sel:DWORD
	v_and_b32_sdwa v34, v28, v65 dst_sel:DWORD dst_unused:UNUSED_PAD src0_sel:WORD_1 src1_sel:DWORD
	v_add3_u32 v31, v31, v36, s47
	v_add3_u32 v30, v30, v42, s47
	v_add3_u32 v28, v28, v34, s47
	v_add3_u32 v29, v29, v32, s47
	v_and_b32_e32 v31, 0xffff0000, v31
	v_and_b32_e32 v30, 0xffff0000, v30
	v_or_b32_sdwa v29, v31, v29 dst_sel:DWORD dst_unused:UNUSED_PAD src0_sel:DWORD src1_sel:WORD_1
	v_or_b32_sdwa v28, v30, v28 dst_sel:DWORD dst_unused:UNUSED_PAD src0_sel:DWORD src1_sel:WORD_1
	global_store_dwordx2 v[52:53], v[28:29], off offset:1024
	v_mov_b32_e32 v36, v43
	v_mov_b32_e32 v32, v35
	v_pk_mul_f32 v[34:35], v[66:67], v[36:37] op_sel_hi:[0,1]
	v_pk_mul_f32 v[32:33], v[66:67], v[32:33] op_sel_hi:[0,1]
	s_waitcnt lgkmcnt(0)
	v_mov_b32_e32 v28, v116
	v_mov_b32_e32 v29, v117
	v_mov_b32_e32 v30, v118
	v_mov_b32_e32 v31, v119
	v_mov_b32_e32 v44, v120
	v_mov_b32_e32 v45, v121
	v_mov_b32_e32 v46, v122
	v_mov_b32_e32 v47, v123
	v_mov_b32_e32 v38, v124
	v_mov_b32_e32 v39, v125
	v_mov_b32_e32 v40, v126
	v_mov_b32_e32 v41, v127
	v_mov_b32_e32 v37, v30
	v_mov_b32_e32 v30, v29
	v_mov_b32_e32 v43, v46
	v_mov_b32_e32 v46, v45
	v_mov_b32_e32 v36, v28
	v_mov_b32_e32 v42, v44
	v_mov_b32_e32 v49, v40
	v_mov_b32_e32 v40, v39
	v_pk_mul_f32 v[30:31], v[32:33], v[30:31]
	v_pk_add_f32 v[32:33], v[46:47], 1.0 op_sel_hi:[1,0]
	v_mov_b32_e32 v48, v38
	v_pk_mul_f32 v[28:29], v[34:35], v[36:37]
	v_pk_add_f32 v[34:35], v[42:43], 1.0 op_sel_hi:[1,0]
	v_pk_fma_f32 v[30:31], v[30:31], v[32:33], v[40:41]
	v_pk_fma_f32 v[28:29], v[28:29], v[34:35], v[48:49]
	v_and_b32_sdwa v34, v31, v65 dst_sel:DWORD dst_unused:UNUSED_PAD src0_sel:WORD_1 src1_sel:DWORD
	v_and_b32_sdwa v35, v30, v65 dst_sel:DWORD dst_unused:UNUSED_PAD src0_sel:WORD_1 src1_sel:DWORD
	v_and_b32_sdwa v32, v29, v65 dst_sel:DWORD dst_unused:UNUSED_PAD src0_sel:WORD_1 src1_sel:DWORD
	v_and_b32_sdwa v33, v28, v65 dst_sel:DWORD dst_unused:UNUSED_PAD src0_sel:WORD_1 src1_sel:DWORD
	v_add3_u32 v31, v31, v34, s47
	v_add3_u32 v30, v30, v35, s47
	v_add3_u32 v28, v28, v33, s47
	v_add3_u32 v29, v29, v32, s47
	v_and_b32_e32 v31, 0xffff0000, v31
	v_and_b32_e32 v30, 0xffff0000, v30
	v_or_b32_sdwa v29, v31, v29 dst_sel:DWORD dst_unused:UNUSED_PAD src0_sel:DWORD src1_sel:WORD_1
	v_or_b32_sdwa v28, v30, v28 dst_sel:DWORD dst_unused:UNUSED_PAD src0_sel:DWORD src1_sel:WORD_1
	global_store_dwordx2 v[52:53], v[28:29], off offset:1536
	s_and_b64 exec, exec, s[0:1]
	s_cbranch_execz .LBB0_908
	v_cndmask_b32_e64 v3, v3, 16, vcc
	v_mul_hi_i32_i24_e32 v33, 0x6000, v3
	v_mul_i32_i24_e32 v32, 0x6000, v3
	v_lshl_add_u64 v[32:33], s[12:13], 0, v[32:33]
	v_lshl_add_u64 v[40:41], v[32:33], 0, s[22:23]
	global_load_dwordx4 v[28:31], v[4:5], off
	v_lshl_add_u64 v[42:43], v[32:33], 0, s[24:25]
	v_lshl_add_u64 v[32:33], v[40:41], 0, v[0:1]
	global_load_dwordx4 v[32:35], v[32:33], off
	v_lshl_add_u64 v[36:37], v[42:43], 0, v[0:1]
	global_load_dwordx4 v[36:39], v[36:37], off
	global_load_dwordx4 v[92:95], v[4:5], off offset:1024
	v_mov_b32_e32 v128, v12
	v_mov_b32_e32 v129, v1
	v_lshl_add_u64 v[130:131], v[40:41], 0, v[128:129]
	global_load_dwordx4 v[96:99], v[130:131], off
	v_mov_b32_e32 v128, v12
	v_mov_b32_e32 v129, v1
	v_lshl_add_u64 v[130:131], v[42:43], 0, v[128:129]
	global_load_dwordx4 v[100:103], v[130:131], off
	global_load_dwordx4 v[104:107], v[4:5], off offset:2048
	v_mov_b32_e32 v128, v14
	v_mov_b32_e32 v129, v1
	v_lshl_add_u64 v[130:131], v[40:41], 0, v[128:129]
	global_load_dwordx4 v[108:111], v[130:131], off
	v_mov_b32_e32 v128, v14
	v_mov_b32_e32 v129, v1
	v_lshl_add_u64 v[130:131], v[42:43], 0, v[128:129]
	global_load_dwordx4 v[112:115], v[130:131], off
	global_load_dwordx4 v[116:119], v[4:5], off offset:3072
	v_mov_b32_e32 v128, v16
	v_mov_b32_e32 v129, v1
	v_lshl_add_u64 v[130:131], v[40:41], 0, v[128:129]
	global_load_dwordx4 v[120:123], v[130:131], off
	v_mov_b32_e32 v128, v16
	v_mov_b32_e32 v129, v1
	v_lshl_add_u64 v[130:131], v[42:43], 0, v[128:129]
	global_load_dwordx4 v[124:127], v[130:131], off
	v_lshlrev_b32_e32 v44, 16, v26
	v_and_b32_e32 v26, 0xffff0000, v26
	v_and_b32_e32 v48, 0xffff0000, v24
	v_lshlrev_b32_e32 v46, 16, v24
	v_lshlrev_b32_e32 v51, 16, v22
	v_and_b32_e32 v53, 0xffff0000, v22
	v_lshlrev_b32_e32 v55, 16, v23
	v_and_b32_e32 v57, 0xffff0000, v23
	v_mov_b32_e32 v22, v26
	v_mov_b32_e32 v23, v48
	v_lshlrev_b32_e32 v45, 16, v27
	v_lshlrev_b32_e32 v47, 16, v25
	v_lshlrev_b32_e32 v50, 16, v20
	v_and_b32_e32 v52, 0xffff0000, v20
	v_lshlrev_b32_e32 v54, 16, v21
	v_and_b32_e32 v56, 0xffff0000, v21
	v_mov_b32_e32 v20, v44
	v_mov_b32_e32 v21, v46
	v_pk_mul_f32 v[22:23], v[22:23], v[22:23]
	v_and_b32_e32 v27, 0xffff0000, v27
	v_and_b32_e32 v49, 0xffff0000, v25
	v_mov_b32_e32 v24, v45
	v_mov_b32_e32 v25, v47
	v_pk_mul_f32 v[60:61], v[52:53], v[52:53]
	v_pk_fma_f32 v[20:21], v[20:21], v[20:21], v[22:23]
	v_mov_b32_e32 v58, v27
	v_mov_b32_e32 v59, v49
	v_pk_fma_f32 v[60:61], v[50:51], v[50:51], v[60:61]
	v_pk_fma_f32 v[20:21], v[24:25], v[24:25], v[20:21]
	v_pk_fma_f32 v[22:23], v[54:55], v[54:55], v[60:61]
	v_pk_fma_f32 v[20:21], v[58:59], v[58:59], v[20:21]
	v_pk_fma_f32 v[22:23], v[56:57], v[56:57], v[22:23]
	v_add_f32_e32 v3, v20, v21
	v_add_f32_e32 v3, v3, v22
	v_add_f32_e32 v3, v3, v23
	s_waitcnt vmcnt(0) lgkmcnt(0)
	v_mov_b32_e32 v24, v28
	v_add_f32_dpp v3, v3, v3 quad_perm:[1,0,3,2] row_mask:0xf bank_mask:0xf bound_ctrl:1
	v_mov_b32_e32 v25, v30
	v_mov_b32_e32 v30, v29
	v_add_f32_dpp v3, v3, v3 quad_perm:[2,3,0,1] row_mask:0xf bank_mask:0xf bound_ctrl:1
	s_nop 1
	v_add_f32_dpp v3, v3, v3 row_half_mirror row_mask:0xf bank_mask:0xf bound_ctrl:1
	s_nop 1
	v_add_f32_dpp v3, v3, v3 row_mirror row_mask:0xf bank_mask:0xf bound_ctrl:1
	s_nop 0
	v_readlane_b32 s2, v3, 16
	v_readlane_b32 s3, v3, 48
	v_readlane_b32 s0, v3, 0
	v_readlane_b32 s1, v3, 32
	v_mov_b32_e32 v20, s2
	v_mov_b32_e32 v21, s3
	v_pk_add_f32 v[20:21], s[0:1], v[20:21]
	s_nop 0
	v_add_f32_e32 v3, v20, v21
	v_fmamk_f32 v3, v3, 0x3a800000, v64
	v_mul_f32_e32 v19, 0x4b800000, v3
	v_cmp_gt_f32_e32 vcc, s46, v3
	s_nop 1
	v_cndmask_b32_e32 v3, v3, v19, vcc
	v_rsq_f32_e32 v3, v3
	v_ashrrev_i32_e32 v19, 31, v18
	v_lshlrev_b64 v[18:19], 11, v[18:19]
	v_mul_f32_e32 v20, 0x45800000, v3
	v_cndmask_b32_e32 v58, v3, v20, vcc
	v_pk_mul_f32 v[20:21], v[58:59], v[44:45] op_sel_hi:[0,1]
	v_pk_mul_f32 v[22:23], v[58:59], v[26:27] op_sel_hi:[0,1]
	v_pk_mul_f32 v[20:21], v[24:25], v[20:21]
	v_mov_b32_e32 v24, v32
	v_mov_b32_e32 v25, v34
	v_mov_b32_e32 v34, v33
	v_pk_mul_f32 v[22:23], v[30:31], v[22:23]
	v_mov_b32_e32 v26, v36
	v_mov_b32_e32 v27, v38
	v_mov_b32_e32 v38, v37
	v_pk_add_f32 v[24:25], v[24:25], 1.0 op_sel_hi:[1,0]
	v_pk_add_f32 v[28:29], v[34:35], 1.0 op_sel_hi:[1,0]
	v_pk_fma_f32 v[20:21], v[24:25], v[20:21], v[26:27]
	v_pk_fma_f32 v[22:23], v[28:29], v[22:23], v[38:39]
	v_and_b32_sdwa v3, v21, v65 dst_sel:DWORD dst_unused:UNUSED_PAD src0_sel:WORD_1 src1_sel:DWORD
	v_and_b32_sdwa v25, v23, v65 dst_sel:DWORD dst_unused:UNUSED_PAD src0_sel:WORD_1 src1_sel:DWORD
	v_and_b32_sdwa v26, v22, v65 dst_sel:DWORD dst_unused:UNUSED_PAD src0_sel:WORD_1 src1_sel:DWORD
	v_and_b32_sdwa v24, v20, v65 dst_sel:DWORD dst_unused:UNUSED_PAD src0_sel:WORD_1 src1_sel:DWORD
	v_add3_u32 v3, v21, v3, s47
	v_add3_u32 v21, v23, v25, s47
	v_add3_u32 v22, v22, v26, s47
	v_add3_u32 v20, v20, v24, s47
	v_and_b32_e32 v21, 0xffff0000, v21
	v_and_b32_e32 v22, 0xffff0000, v22
	v_or_b32_sdwa v21, v21, v3 dst_sel:DWORD dst_unused:UNUSED_PAD src0_sel:DWORD src1_sel:WORD_1
	v_or_b32_sdwa v20, v22, v20 dst_sel:DWORD dst_unused:UNUSED_PAD src0_sel:DWORD src1_sel:WORD_1
	v_lshl_add_u64 v[30:31], v[6:7], 0, v[18:19]
	global_store_dwordx2 v[30:31], v[20:21], off
	v_lshl_add_u64 v[22:23], v[40:41], 0, v[12:13]
	v_lshl_add_u64 v[26:27], v[42:43], 0, v[12:13]
	v_pk_mul_f32 v[32:33], v[58:59], v[46:47] op_sel_hi:[0,1]
	v_pk_mul_f32 v[34:35], v[58:59], v[48:49] op_sel_hi:[0,1]
	s_waitcnt lgkmcnt(0)
	v_mov_b32_e32 v18, v92
	v_mov_b32_e32 v19, v93
	v_mov_b32_e32 v20, v94
	v_mov_b32_e32 v21, v95
	v_mov_b32_e32 v22, v96
	v_mov_b32_e32 v23, v97
	v_mov_b32_e32 v24, v98
	v_mov_b32_e32 v25, v99
	v_mov_b32_e32 v26, v100
	v_mov_b32_e32 v27, v101
	v_mov_b32_e32 v28, v102
	v_mov_b32_e32 v29, v103
	v_mov_b32_e32 v36, v18
	v_mov_b32_e32 v37, v20
	v_mov_b32_e32 v38, v22
	v_mov_b32_e32 v39, v24
	v_mov_b32_e32 v20, v19
	v_mov_b32_e32 v24, v23
	v_mov_b32_e32 v44, v26
	v_mov_b32_e32 v45, v28
	v_mov_b32_e32 v28, v27
	v_pk_mul_f32 v[18:19], v[32:33], v[36:37]
	v_pk_add_f32 v[22:23], v[38:39], 1.0 op_sel_hi:[1,0]
	v_pk_mul_f32 v[20:21], v[34:35], v[20:21]
	v_pk_add_f32 v[24:25], v[24:25], 1.0 op_sel_hi:[1,0]
	v_pk_fma_f32 v[18:19], v[18:19], v[22:23], v[44:45]
	v_pk_fma_f32 v[20:21], v[20:21], v[24:25], v[28:29]
	v_and_b32_sdwa v3, v19, v65 dst_sel:DWORD dst_unused:UNUSED_PAD src0_sel:WORD_1 src1_sel:DWORD
	v_and_b32_sdwa v13, v18, v65 dst_sel:DWORD dst_unused:UNUSED_PAD src0_sel:WORD_1 src1_sel:DWORD
	v_and_b32_sdwa v22, v21, v65 dst_sel:DWORD dst_unused:UNUSED_PAD src0_sel:WORD_1 src1_sel:DWORD
	v_and_b32_sdwa v23, v20, v65 dst_sel:DWORD dst_unused:UNUSED_PAD src0_sel:WORD_1 src1_sel:DWORD
	v_add3_u32 v13, v18, v13, s47
	v_add3_u32 v3, v19, v3, s47
	v_add3_u32 v18, v21, v22, s47
	v_add3_u32 v19, v20, v23, s47
	v_and_b32_e32 v18, 0xffff0000, v18
	v_and_b32_e32 v20, 0xffff0000, v19
	v_or_b32_sdwa v19, v18, v3 dst_sel:DWORD dst_unused:UNUSED_PAD src0_sel:DWORD src1_sel:WORD_1
	v_or_b32_sdwa v18, v20, v13 dst_sel:DWORD dst_unused:UNUSED_PAD src0_sel:DWORD src1_sel:WORD_1
	global_store_dwordx2 v[30:31], v[18:19], off offset:512
	v_lshl_add_u64 v[22:23], v[40:41], 0, v[14:15]
	v_lshl_add_u64 v[26:27], v[42:43], 0, v[14:15]
	v_mov_b32_e32 v32, v50
	v_mov_b32_e32 v33, v54
	v_mov_b32_e32 v34, v52
	v_mov_b32_e32 v35, v56
	v_pk_mul_f32 v[32:33], v[58:59], v[32:33] op_sel_hi:[0,1]
	v_pk_mul_f32 v[34:35], v[58:59], v[34:35] op_sel_hi:[0,1]
	v_mov_b32_e32 v56, v53
	v_mov_b32_e32 v54, v51
	s_waitcnt lgkmcnt(0)
	v_mov_b32_e32 v18, v104
	v_mov_b32_e32 v19, v105
	v_mov_b32_e32 v20, v106
	v_mov_b32_e32 v21, v107
	v_mov_b32_e32 v22, v108
	v_mov_b32_e32 v23, v109
	v_mov_b32_e32 v24, v110
	v_mov_b32_e32 v25, v111
	v_mov_b32_e32 v26, v112
	v_mov_b32_e32 v27, v113
	v_mov_b32_e32 v28, v114
	v_mov_b32_e32 v29, v115
	v_mov_b32_e32 v36, v18
	v_mov_b32_e32 v37, v20
	v_mov_b32_e32 v38, v22
	v_mov_b32_e32 v39, v24
	v_mov_b32_e32 v20, v19
	v_mov_b32_e32 v24, v23
	v_mov_b32_e32 v44, v26
	v_mov_b32_e32 v45, v28
	v_mov_b32_e32 v28, v27
	v_pk_mul_f32 v[18:19], v[32:33], v[36:37]
	v_pk_add_f32 v[22:23], v[38:39], 1.0 op_sel_hi:[1,0]
	v_pk_mul_f32 v[20:21], v[34:35], v[20:21]
	v_pk_add_f32 v[24:25], v[24:25], 1.0 op_sel_hi:[1,0]
	v_pk_fma_f32 v[18:19], v[18:19], v[22:23], v[44:45]
	v_pk_fma_f32 v[20:21], v[20:21], v[24:25], v[28:29]
	v_and_b32_sdwa v13, v18, v65 dst_sel:DWORD dst_unused:UNUSED_PAD src0_sel:WORD_1 src1_sel:DWORD
	v_and_b32_sdwa v15, v21, v65 dst_sel:DWORD dst_unused:UNUSED_PAD src0_sel:WORD_1 src1_sel:DWORD
	v_and_b32_sdwa v22, v20, v65 dst_sel:DWORD dst_unused:UNUSED_PAD src0_sel:WORD_1 src1_sel:DWORD
	v_and_b32_sdwa v3, v19, v65 dst_sel:DWORD dst_unused:UNUSED_PAD src0_sel:WORD_1 src1_sel:DWORD
	v_add3_u32 v13, v18, v13, s47
	v_add3_u32 v15, v21, v15, s47
	v_add3_u32 v18, v20, v22, s47
	v_add3_u32 v3, v19, v3, s47
	v_and_b32_e32 v15, 0xffff0000, v15
	v_and_b32_e32 v18, 0xffff0000, v18
	v_or_b32_sdwa v19, v15, v3 dst_sel:DWORD dst_unused:UNUSED_PAD src0_sel:DWORD src1_sel:WORD_1
	v_or_b32_sdwa v18, v18, v13 dst_sel:DWORD dst_unused:UNUSED_PAD src0_sel:DWORD src1_sel:WORD_1
	global_store_dwordx2 v[30:31], v[18:19], off offset:1024
	v_lshl_add_u64 v[22:23], v[40:41], 0, v[16:17]
	v_lshl_add_u64 v[26:27], v[42:43], 0, v[16:17]
	v_pk_mul_f32 v[34:35], v[58:59], v[56:57] op_sel_hi:[0,1]
	v_pk_mul_f32 v[32:33], v[58:59], v[54:55] op_sel_hi:[0,1]
	s_waitcnt lgkmcnt(0)
	v_mov_b32_e32 v18, v116
	v_mov_b32_e32 v19, v117
	v_mov_b32_e32 v20, v118
	v_mov_b32_e32 v21, v119
	v_mov_b32_e32 v22, v120
	v_mov_b32_e32 v23, v121
	v_mov_b32_e32 v24, v122
	v_mov_b32_e32 v25, v123
	v_mov_b32_e32 v26, v124
	v_mov_b32_e32 v27, v125
	v_mov_b32_e32 v28, v126
	v_mov_b32_e32 v29, v127
	v_mov_b32_e32 v37, v20
	v_mov_b32_e32 v20, v19
	v_mov_b32_e32 v39, v24
	v_mov_b32_e32 v24, v23
	v_mov_b32_e32 v36, v18
	v_mov_b32_e32 v38, v22
	v_mov_b32_e32 v41, v28
	v_mov_b32_e32 v28, v27
	v_pk_mul_f32 v[20:21], v[34:35], v[20:21]
	v_pk_add_f32 v[24:25], v[24:25], 1.0 op_sel_hi:[1,0]
	v_mov_b32_e32 v40, v26
	v_pk_mul_f32 v[18:19], v[32:33], v[36:37]
	v_pk_add_f32 v[22:23], v[38:39], 1.0 op_sel_hi:[1,0]
	v_pk_fma_f32 v[20:21], v[20:21], v[24:25], v[28:29]
	v_pk_fma_f32 v[18:19], v[18:19], v[22:23], v[40:41]
	v_and_b32_sdwa v15, v21, v65 dst_sel:DWORD dst_unused:UNUSED_PAD src0_sel:WORD_1 src1_sel:DWORD
	v_and_b32_sdwa v17, v20, v65 dst_sel:DWORD dst_unused:UNUSED_PAD src0_sel:WORD_1 src1_sel:DWORD
	v_and_b32_sdwa v3, v19, v65 dst_sel:DWORD dst_unused:UNUSED_PAD src0_sel:WORD_1 src1_sel:DWORD
	v_and_b32_sdwa v13, v18, v65 dst_sel:DWORD dst_unused:UNUSED_PAD src0_sel:WORD_1 src1_sel:DWORD
	v_add3_u32 v15, v21, v15, s47
	v_add3_u32 v17, v20, v17, s47
	v_add3_u32 v13, v18, v13, s47
	v_add3_u32 v3, v19, v3, s47
	v_and_b32_e32 v15, 0xffff0000, v15
	v_and_b32_e32 v17, 0xffff0000, v17
	v_or_b32_sdwa v19, v15, v3 dst_sel:DWORD dst_unused:UNUSED_PAD src0_sel:DWORD src1_sel:WORD_1
	v_or_b32_sdwa v18, v17, v13 dst_sel:DWORD dst_unused:UNUSED_PAD src0_sel:DWORD src1_sel:WORD_1
	global_store_dwordx2 v[30:31], v[18:19], off offset:1536
	s_branch .LBB0_908
